# scan: raw tile load issues all nine 16-byte loads before one wait (was load-wait-write per piece)
# speedup vs baseline: 1.0178x; 1.0063x over previous
; __device__ __forceinline__ int tid_opaque(int wv) { return wv * 64 + lane_fresh(); }
; __device__ __forceinline__ void scan_mfma(PP p, unsigned char* shm, int wv) {
;     ...
;             const int tid = tid_opaque(wv);
;             bf16_t* raw = (bf16_t*)(shm + 66560);
; #pragma unroll
;             for (int i = 0; i < 9; ++i) {
;                 const int piece = tid + 512 * i;
;                 if (piece < 67 * 64) {
;                     const int row = piece >> 6, c8 = piece & 63, tt = t0 - 2 + row;
;                     u32x4 v = {0u, 0u, 0u, 0u};
;                     if (tt >= 0 && tt < seqlen) v = *(const u32x4*)(proj + (size_t)(seqbase + tt) * DIN + 8 * c8);
;                     *(u32x4*)(raw + row * 512 + 8 * c8) = v;
;                 }
;             }
.LBB0_332:
	s_add_i32 s4, s78, 0xfffffe00
	s_lshr_b32 s5, s4, 2
	s_addk_i32 s5, 0x200
	s_lshl_b32 s4, s78, 6
	s_lshl_b32 s35, s5, 6
	s_and_b32 s34, s4, 0x3fc0
	s_and_b32 s36, s35, 0xc0
	s_and_b64 s[30:31], s[22:23], exec
	s_mov_b32 s30, -1
	s_cselect_b32 s38, s34, s36
	v_mbcnt_lo_u32_b32 v0, s30, 0
	v_mbcnt_hi_u32_b32 v0, s30, v0
	v_add_u32_e32 v54, s33, v0
	v_lshlrev_b32_e32 v0, 4, v0
	s_cselect_b32 s4, s4, s35
	v_and_b32_e32 v0, 0x3f0, v0
	s_cselect_b32 s37, 0x4000, s64
	s_sub_i32 s36, s4, s38
	s_add_i32 s38, s38, -2
	v_lshl_add_u64 v[38:39], s[10:11], 0, v[0:1]
	v_add_u32_e32 v0, s65, v0
	s_mov_b64 s[30:31], exec
	v_ashrrev_i32_e32 v95, 6, v54
	v_add_u32_e32 v96, s38, v95
	v_lshl_add_u32 v86, v95, 10, v0
	v_mov_b32_e32 v2, 0
	v_mov_b32_e32 v3, 0
	v_mov_b32_e32 v4, 0
	v_mov_b32_e32 v5, 0
	v_cmp_gt_u32_e32 vcc, s37, v96
	v_cmp_gt_i32_e64 s[34:35], s66, v54
	s_and_b64 vcc, vcc, s[34:35]
	s_and_b64 exec, s[30:31], vcc
	v_add_u32_e32 v97, s36, v96
	v_mad_i64_i32 v[98:99], s[40:41], v97, s67, v[38:39]
	global_load_dwordx4 v[2:5], v[98:99], off
	s_mov_b64 exec, s[30:31]
	v_add_u32_e32 v95, 0x200, v54
	v_ashrrev_i32_e32 v95, 6, v95
	v_add_u32_e32 v96, s38, v95
	v_lshl_add_u32 v87, v95, 10, v0
	v_mov_b32_e32 v6, 0
	v_mov_b32_e32 v7, 0
	v_mov_b32_e32 v8, 0
	v_mov_b32_e32 v9, 0
	v_cmp_gt_u32_e32 vcc, s37, v96
	v_cmp_gt_i32_e64 s[34:35], s68, v54
	s_and_b64 vcc, vcc, s[34:35]
	s_and_b64 exec, s[30:31], vcc
	v_add_u32_e32 v97, s36, v96
	v_mad_i64_i32 v[98:99], s[40:41], v97, s67, v[38:39]
	global_load_dwordx4 v[6:9], v[98:99], off
	s_mov_b64 exec, s[30:31]
	v_add_u32_e32 v95, 0x400, v54
	v_ashrrev_i32_e32 v95, 6, v95
	v_add_u32_e32 v96, s38, v95
	v_lshl_add_u32 v88, v95, 10, v0
	v_mov_b32_e32 v10, 0
	v_mov_b32_e32 v11, 0
	v_mov_b32_e32 v12, 0
	v_mov_b32_e32 v13, 0
	v_cmp_gt_u32_e32 vcc, s37, v96
	v_cmp_gt_i32_e64 s[34:35], s69, v54
	s_and_b64 vcc, vcc, s[34:35]
	s_and_b64 exec, s[30:31], vcc
	v_add_u32_e32 v97, s36, v96
	v_mad_i64_i32 v[98:99], s[40:41], v97, s67, v[38:39]
	global_load_dwordx4 v[10:13], v[98:99], off
	s_mov_b64 exec, s[30:31]
	v_add_u32_e32 v95, 0x600, v54
	v_ashrrev_i32_e32 v95, 6, v95
	v_add_u32_e32 v96, s38, v95
	v_lshl_add_u32 v89, v95, 10, v0
	v_mov_b32_e32 v14, 0
	v_mov_b32_e32 v15, 0
	v_mov_b32_e32 v16, 0
	v_mov_b32_e32 v17, 0
	v_cmp_gt_u32_e32 vcc, s37, v96
	v_cmp_gt_i32_e64 s[34:35], s70, v54
	s_and_b64 vcc, vcc, s[34:35]
	s_and_b64 exec, s[30:31], vcc
	v_add_u32_e32 v97, s36, v96
	v_mad_i64_i32 v[98:99], s[40:41], v97, s67, v[38:39]
	global_load_dwordx4 v[14:17], v[98:99], off
	s_mov_b64 exec, s[30:31]
	v_add_u32_e32 v95, 0x800, v54
	v_ashrrev_i32_e32 v95, 6, v95
	v_add_u32_e32 v96, s38, v95
	v_lshl_add_u32 v90, v95, 10, v0
	v_mov_b32_e32 v18, 0
	v_mov_b32_e32 v19, 0
	v_mov_b32_e32 v20, 0
	v_mov_b32_e32 v21, 0
	v_cmp_gt_u32_e32 vcc, s37, v96
	v_cmp_gt_i32_e64 s[34:35], s71, v54
	s_and_b64 vcc, vcc, s[34:35]
	s_and_b64 exec, s[30:31], vcc
	v_add_u32_e32 v97, s36, v96
	v_mad_i64_i32 v[98:99], s[40:41], v97, s67, v[38:39]
	global_load_dwordx4 v[18:21], v[98:99], off
	s_mov_b64 exec, s[30:31]
	v_add_u32_e32 v95, 0xa00, v54
	v_ashrrev_i32_e32 v95, 6, v95
	v_add_u32_e32 v96, s38, v95
	v_lshl_add_u32 v91, v95, 10, v0
	v_mov_b32_e32 v22, 0
	v_mov_b32_e32 v23, 0
	v_mov_b32_e32 v24, 0
	v_mov_b32_e32 v25, 0
	v_cmp_gt_u32_e32 vcc, s37, v96
	v_cmp_gt_i32_e64 s[34:35], s72, v54
	s_and_b64 vcc, vcc, s[34:35]
	s_and_b64 exec, s[30:31], vcc
	v_add_u32_e32 v97, s36, v96
	v_mad_i64_i32 v[98:99], s[40:41], v97, s67, v[38:39]
	global_load_dwordx4 v[22:25], v[98:99], off
	s_mov_b64 exec, s[30:31]
	v_add_u32_e32 v95, 0xc00, v54
	v_ashrrev_i32_e32 v95, 6, v95
	v_add_u32_e32 v96, s38, v95
	v_lshl_add_u32 v92, v95, 10, v0
	v_mov_b32_e32 v26, 0
	v_mov_b32_e32 v27, 0
	v_mov_b32_e32 v28, 0
	v_mov_b32_e32 v29, 0
	v_cmp_gt_u32_e32 vcc, s37, v96
	v_cmp_gt_i32_e64 s[34:35], s73, v54
	s_and_b64 vcc, vcc, s[34:35]
	s_and_b64 exec, s[30:31], vcc
	v_add_u32_e32 v97, s36, v96
	v_mad_i64_i32 v[98:99], s[40:41], v97, s67, v[38:39]
	global_load_dwordx4 v[26:29], v[98:99], off
	s_mov_b64 exec, s[30:31]
	v_add_u32_e32 v95, 0xe00, v54
	v_ashrrev_i32_e32 v95, 6, v95
	v_add_u32_e32 v96, s38, v95
	v_lshl_add_u32 v93, v95, 10, v0
	v_mov_b32_e32 v30, 0
	v_mov_b32_e32 v31, 0
	v_mov_b32_e32 v32, 0
	v_mov_b32_e32 v33, 0
	v_cmp_gt_u32_e32 vcc, s37, v96
	v_cmp_gt_i32_e64 s[34:35], s74, v54
	s_and_b64 vcc, vcc, s[34:35]
	s_and_b64 exec, s[30:31], vcc
	v_add_u32_e32 v97, s36, v96
	v_mad_i64_i32 v[98:99], s[40:41], v97, s67, v[38:39]
	global_load_dwordx4 v[30:33], v[98:99], off
	s_mov_b64 exec, s[30:31]
	v_add_u32_e32 v95, 0x1000, v54
	v_ashrrev_i32_e32 v95, 6, v95
	v_add_u32_e32 v96, s38, v95
	v_lshl_add_u32 v94, v95, 10, v0
	v_mov_b32_e32 v82, 0
	v_mov_b32_e32 v83, 0
	v_mov_b32_e32 v84, 0
	v_mov_b32_e32 v85, 0
	v_cmp_gt_u32_e32 vcc, s37, v96
	v_cmp_gt_i32_e64 s[34:35], s61, v54
	s_and_b64 vcc, vcc, s[34:35]
	s_and_b64 exec, s[30:31], vcc
	v_add_u32_e32 v97, s36, v96
	v_mad_i64_i32 v[98:99], s[40:41], v97, s67, v[38:39]
	global_load_dwordx4 v[82:85], v[98:99], off
	s_mov_b64 exec, s[30:31]
	s_waitcnt vmcnt(0)
	v_cmp_gt_i32_e32 vcc, s66, v54
	s_and_b64 exec, s[30:31], vcc
	ds_write_b128 v86, v[2:5]
	v_cmp_gt_i32_e32 vcc, s68, v54
	s_and_b64 exec, s[30:31], vcc
	ds_write_b128 v87, v[6:9]
	v_cmp_gt_i32_e32 vcc, s69, v54
	s_and_b64 exec, s[30:31], vcc
	ds_write_b128 v88, v[10:13]
	v_cmp_gt_i32_e32 vcc, s70, v54
	s_and_b64 exec, s[30:31], vcc
	ds_write_b128 v89, v[14:17]
	v_cmp_gt_i32_e32 vcc, s71, v54
	s_and_b64 exec, s[30:31], vcc
	ds_write_b128 v90, v[18:21]
	v_cmp_gt_i32_e32 vcc, s72, v54
	s_and_b64 exec, s[30:31], vcc
	ds_write_b128 v91, v[22:25]
	v_cmp_gt_i32_e32 vcc, s73, v54
	s_and_b64 exec, s[30:31], vcc
	ds_write_b128 v92, v[26:29]
	v_cmp_gt_i32_e32 vcc, s74, v54
	s_and_b64 exec, s[30:31], vcc
	ds_write_b128 v93, v[30:33]
	v_cmp_gt_i32_e32 vcc, s61, v54
	s_and_b64 exec, s[30:31], vcc
	ds_write_b128 v94, v[82:85]
	s_mov_b64 exec, s[30:31]
